# GEMM3: additional one-time per-block start skew (0..3 x s_sleep 16 by blockIdx bits 1-2) so tile boundaries stay de-phased across blocks
# baseline (speedup 1.0000x reference)
.Lmy_g3_go:
	v_readlane_b32 s99, v255, 46
	s_nop 3
	s_bfe_u32 s99, s99, 0x20001
	s_cmp_eq_u32 s99, 0
	s_cbranch_scc1 .Lmy_g3_skew_done
.Lmy_g3_skew:
	s_sleep 16
	s_sub_u32 s99, s99, 1
	s_cmp_lg_u32 s99, 0
	s_cbranch_scc1 .Lmy_g3_skew
